# v52 + scan step B: inverse-chain K=16 products on v_mfma_f32_16x16x16_f16 (11 zero-fill v_mov removed), operand fragments loaded straight into MFMA operand registers (25 v_mov shuffles removed), count
# speedup vs baseline: 1.0001x; 1.0001x over previous
.LBB0_573:
	s_waitcnt lgkmcnt(0)
	s_barrier
	s_and_b64 vcc, exec, s[24:25]
	s_cbranch_vccnz .LBB0_578
	v_add_u32_e32 v8, s71, v125
	ds_read_b64 v[24:25], v8
	ds_read_b64 v[26:27], v154
	ds_read_b64 v[20:21], v8 offset:4608
	ds_read_b64 v[22:23], v154 offset:4608
	ds_read_b64 v[32:33], v155
	ds_read_b64 v[34:35], v156
	ds_read_b64 v[28:29], v155 offset:4608
	ds_read_b64 v[30:31], v156 offset:4608
	s_mov_b64 s[24:25], -1
	s_and_b64 vcc, exec, s[30:31]
	s_waitcnt lgkmcnt(0)
	s_cbranch_vccz .LBB0_576
	ds_read_b64 v[82:83], v8 offset:6912
	ds_read_b64 v[84:85], v154 offset:6912
	ds_read_b64 v[36:37], v8 offset:2304
	ds_read_b64 v[38:39], v154 offset:2304
	ds_read_b64 v[166:167], v155 offset:6912
	ds_read_b64 v[168:169], v156 offset:6912
	ds_read_b64 v[158:159], v155 offset:2304
	ds_read_b64 v[160:161], v156 offset:2304
	s_waitcnt lgkmcnt(6)
	v_mfma_f32_16x16x32_f16 v[162:165], v[82:85], v[24:27], 0
	s_or_b64 vcc, s[18:19], s[14:15]
	s_mov_b64 s[24:25], 0
	s_waitcnt lgkmcnt(4)
	v_mfma_f32_16x16x32_f16 v[40:43], v[82:85], v[36:39], 0
	v_mfma_f32_16x16x32_f16 v[36:39], v[20:23], v[36:39], 0
	v_mov_b32_e32 v8, s39
	s_waitcnt lgkmcnt(2)
	v_mfma_f32_16x16x32_f16 v[162:165], v[166:169], v[32:35], v[162:165]
	s_waitcnt lgkmcnt(0)
	v_mfma_f32_16x16x32_f16 v[40:43], v[166:169], v[158:161], v[40:43]
	v_mov_b32_e32 v82, s39
	v_add_u32_e32 v84, s71, v103
	v_mfma_f32_16x16x32_f16 v[36:39], v[28:31], v[158:161], v[36:39]
	s_nop 4
	v_cndmask_b32_e64 v8, v40, v8, s[10:11]
	s_nop 1
	v_cndmask_b32_e64 v9, v36, v82, s[10:11]
	v_cndmask_b32_e64 v11, v8, v40, s[8:9]
	v_cndmask_b32_e32 v8, 0, v164, vcc
	s_or_b64 vcc, vcc, s[12:13]
	v_cndmask_b32_e64 v40, 0, v41, s[8:9]
	v_cndmask_b32_e64 v41, v9, v36, s[8:9]
	v_cndmask_b32_e32 v36, 0, v163, vcc
	s_or_b64 vcc, vcc, s[8:9]
	v_cndmask_b32_e64 v82, 0, v37, s[8:9]
	v_cndmask_b32_e32 v37, 0, v162, vcc
	v_cndmask_b32_e64 v9, 0, v165, s[18:19]
	v_cvt_pk_f16_f32 v9, v8, v9
	v_cvt_pk_f16_f32 v8, v37, v36
	ds_read2st64_b32 v[36:37], v104 offset0:53 offset1:54
	v_cndmask_b32_e64 v42, v42, 0, s[16:17]
	v_cndmask_b32_e64 v83, v38, 0, s[16:17]
	v_cndmask_b32_e64 v38, v43, 0, s[20:21]
	v_cndmask_b32_e64 v43, v39, 0, s[20:21]
	v_cvt_pk_f16_f32 v39, v42, v38
	v_cvt_pk_f16_f32 v38, v11, v40
	v_add_u32_e32 v11, 0x100, v84
	ds_write2st64_b64 v11, v[8:9], v[38:39] offset0:22 offset1:23
	s_waitcnt lgkmcnt(1)
	v_sub_f32_e32 v8, v37, v36
	v_exp_f32_e32 v11, v36
	v_exp_f32_e32 v36, v8
	v_cvt_pk_f16_f32 v9, v83, v43
	v_cvt_pk_f16_f32 v8, v41, v82
	ds_write_b64 v84, v[8:9] offset:12544
	ds_write2st64_b32 v104, v11, v36 offset0:53 offset1:54
.LBB0_576:
	s_andn2_b64 vcc, exec, s[24:25]
	s_cbranch_vccnz .LBB0_578
	v_mfma_f32_16x16x32_f16 v[36:39], v[20:23], v[24:27], 0
	v_mfma_f32_16x16x32_f16 v[20:23], v[24:27], v[20:23], 0
	v_mfma_f32_16x16x32_f16 v[24:27], v[28:31], v[32:35], v[36:39]
	v_mfma_f32_16x16x32_f16 v[20:23], v[32:35], v[28:31], v[20:23]
	s_nop 6
	v_cndmask_b32_e64 v36, 0, -v24, s[8:9]
	v_cndmask_b32_e64 v37, 0, -v25, s[12:13]
	v_cndmask_b32_e64 v32, 0, -v26, s[14:15]
	v_cndmask_b32_e64 v33, 0, -v27, s[18:19]
	v_cndmask_b32_e64 v28, 0, -v20, s[10:11]
	v_cndmask_b32_e64 v29, -v21, 0, s[8:9]
	v_cndmask_b32_e64 v30, 0, -v22, s[16:17]
	v_cndmask_b32_e64 v31, 0, -v23, s[20:21]
	v_cvt_pk_f16_f32 v9, v32, v33
	v_cvt_pk_f16_f32 v8, v36, v37
	v_cvt_pk_f16_f32 v21, v30, v31
	v_cvt_pk_f16_f32 v20, v28, v29
	v_pk_add_f32 v[30:31], v[64:65], v[30:31]
	v_pk_add_f32 v[28:29], v[62:63], v[28:29]
	v_mfma_f32_16x16x16_f16 v[24:27], v[8:9], v[20:21], 0
	v_add_f32_e64 v34, v64, v32
	v_add_f32_e64 v35, v65, v33
	v_pk_add_f32 v[32:33], v[62:63], v[36:37]
	v_mfma_f32_16x16x16_f16 v[20:23], v[20:21], v[8:9], 0
	s_nop 3
	v_cvt_pk_f16_f32 v37, v26, v27
	s_nop 2
	v_cvt_pk_f16_f32 v9, v22, v23
	v_cvt_pk_f16_f32 v8, v20, v21
	v_cvt_pk_f16_f32 v21, v30, v31
	v_cvt_pk_f16_f32 v20, v28, v29
	v_cvt_pk_f16_f32 v36, v24, v25
	s_nop 0
	v_mfma_f32_16x16x16_f16 v[28:31], v[8:9], v[20:21], v[28:31]
	v_mfma_f32_16x16x16_f16 v[20:23], v[20:21], v[8:9], v[32:35]
	v_mfma_f32_16x16x16_f16 v[32:35], v[36:37], v[8:9], 0
	v_mfma_f32_16x16x16_f16 v[24:27], v[8:9], v[36:37], 0
	s_nop 6
	v_cvt_pk_f16_f32 v9, v34, v35
	v_cvt_pk_f16_f32 v8, v32, v33
	v_cvt_pk_f16_f32 v33, v30, v31
	v_cvt_pk_f16_f32 v32, v28, v29
	v_cvt_pk_f16_f32 v37, v26, v27
	v_cvt_pk_f16_f32 v36, v24, v25
	v_mfma_f32_16x16x16_f16 v[28:31], v[8:9], v[32:33], v[28:31]
	v_mfma_f32_16x16x16_f16 v[20:23], v[32:33], v[8:9], v[20:23]
	v_mfma_f32_16x16x16_f16 v[24:27], v[36:37], v[8:9], 0
	s_nop 5
	v_cvt_pk_f16_f32 v9, v30, v31
	v_cvt_pk_f16_f32 v8, v28, v29
	v_cvt_pk_f16_f32 v27, v26, v27
	v_cvt_pk_f16_f32 v26, v24, v25
	s_nop 1
	v_mfma_f32_16x16x16_f16 v[20:23], v[8:9], v[26:27], v[20:23]
	s_nop 7
	v_cvt_pk_f16_f32 v9, v22, v23
	v_cvt_pk_f16_f32 v8, v20, v21
	ds_write_b64 v148, v[8:9] offset:13056
